# layer-1 input projection: tile order changed so the V column tiles (costly transposed-store epilogue) go to workgroups with two tiles instead of the three-tile workgroups
# speedup vs baseline: 1.0019x; 1.0019x over previous
.LBB0_60:
	s_ashr_i32 s0, s8, 3
	s_add_i32 s0, s14, s0
	s_abs_i32 s8, s0
	v_readlane_b32 s9, v254, 45
	s_mul_hi_u32 s9, s8, s9
	s_mul_i32 s14, s9, s69
	s_sub_i32 s8, s8, s14
	s_ashr_i32 s1, s0, 31
	s_add_i32 s14, s9, 1
	s_sub_i32 s15, s8, s69
	s_cmp_ge_u32 s8, s69
	s_cselect_b32 s9, s14, s9
	s_cselect_b32 s8, s15, s8
	s_add_i32 s14, s9, 1
	s_cmp_ge_u32 s8, s69
	s_cselect_b32 s8, s14, s9
	s_xor_b32 s8, s8, s1
	s_sub_i32 s1, s8, s1
	s_lshl_b32 s8, s1, 3
	v_readlane_b32 s9, v253, 61
	s_sub_i32 s9, s9, s8
	s_min_i32 s9, s9, 8
	s_abs_i32 s14, s9
	v_cvt_f32_u32_e32 v0, s14
	s_sub_i32 s17, 0, s14
	s_mul_i32 s1, s1, s69
	s_sub_i32 s0, s0, s1
	v_rcp_iflag_f32_e32 v0, v0
	s_abs_i32 s1, s0
	s_xor_b32 s15, s0, s9
	s_ashr_i32 s15, s15, 31
	v_mul_f32_e32 v0, 0x4f7ffffe, v0
	v_cvt_u32_f32_e32 v0, v0
	s_nop 0
	v_readfirstlane_b32 s18, v0
	s_mul_i32 s17, s17, s18
	s_mul_hi_u32 s17, s18, s17
	s_add_i32 s18, s18, s17
	s_mul_hi_u32 s17, s1, s18
	s_mul_i32 s18, s17, s14
	s_sub_i32 s1, s1, s18
	s_add_i32 s18, s17, 1
	s_sub_i32 s22, s1, s14
	s_cmp_ge_u32 s1, s14
	s_cselect_b32 s17, s18, s17
	s_cselect_b32 s1, s22, s1
	s_add_i32 s18, s17, 1
	s_cmp_ge_u32 s1, s14
	s_cselect_b32 s1, s18, s17
	s_xor_b32 s1, s1, s15
	s_sub_i32 s14, s1, s15
	s_mul_i32 s1, s14, s9
	s_sub_i32 s0, s0, s1
	s_add_i32 s97, s0, s8
	s_add_i32 s0, s14, 1
	s_cmp_lg_u32 s14, 8
	s_cselect_b32 s8, s0, 0
	v_readlane_b32 s0, v253, 55
	s_cmp_eq_u32 s0, 1
	s_cbranch_scc0 .Lpn_keep
	s_sub_i32 s0, s8, 5
	s_cmp_lt_u32 s0, 4
	s_cbranch_scc0 .Lpn_keep
	s_xor_b32 s0, s0, 2
	s_add_i32 s8, s0, 5
.Lpn_keep:
	v_readlane_b32 s0, v254, 23
	v_readlane_b32 s1, v254, 24
	s_and_b64 s[0:1], s[0:1], exec
	s_cselect_b32 s18, s8, s14
	s_mov_b64 s[14:15], -1
